# grid barriers 2-8 replaced by a two-level (8 groups) arrive tree with a separate release word in the zeroed control region; first barrier unchanged
# speedup vs baseline: 1.0372x; 1.0277x over previous
; #define SEAM(k) do { if (IN(k) && IN((k) + 1)) grid.sync(); } while (0)
; __global__ void __launch_bounds__(512, 2) mega(Args args) {
;     ...
;     SEAM(1);
.LBB0_187:
	v_readlane_b32 s4, v252, 22
	v_readlane_b32 s7, v252, 25
	s_cmp_gt_i32 s7, 2
	s_cselect_b64 s[0:1], -1, 0
	s_and_b64 s[2:3], s[2:3], s[0:1]
	s_andn2_b64 vcc, exec, s[2:3]
	v_readlane_b32 s5, v252, 23
	v_readlane_b32 s6, v252, 24
	s_cbranch_vccnz .LBB0_199
	v_or_b32_e32 v0, v213, v177
	s_movk_i32 s2, 0x3ff
	v_and_or_b32 v0, v0, s2, v176
	v_cmp_eq_u32_e32 vcc, 0, v0
	s_waitcnt vmcnt(0)
	s_barrier
	s_and_saveexec_b64 s[2:3], vcc
	s_cbranch_execz .LBB0_198
	buffer_wbl2 sc1
	s_waitcnt vmcnt(0)
	v_readlane_b32 s4, v252, 22
	v_readlane_b32 s5, v252, 23
	s_and_b32 s6, s95, 7
	s_lshl_b32 s7, s6, 8
	s_add_i32 s7, s7, 0x80
	v_mov_b32_e32 v0, s7
	v_mov_b32_e32 v1, 1
	s_nop 3
	global_atomic_add v2, v0, v1, s[4:5] sc0
	s_sub_i32 s8, s76, s6
	s_add_i32 s8, s8, 7
	s_lshr_b32 s8, s8, 3
	s_mul_i32 s8, s8, 1
	s_waitcnt vmcnt(0)
	v_readfirstlane_b32 s9, v2
	s_nop 3
	s_add_i32 s9, s9, 1
	s_cmp_lg_u32 s9, s8
	s_cbranch_scc1 .Lgb1_poll
	v_mov_b32_e32 v0, 0x880
	global_atomic_add v2, v0, v1, s[4:5] sc0
	s_waitcnt vmcnt(0)
	v_readfirstlane_b32 s9, v2
	s_nop 3
	s_add_i32 s9, s9, 1
	s_cmp_lg_u32 s9, 8
	s_cbranch_scc1 .Lgb1_poll
	v_mov_b32_e32 v0, 0x980
	s_nop 0
	global_atomic_add v0, v1, s[4:5]
.Lgb1_poll:
	v_mov_b32_e32 v0, 0x980
.Lgb1_loop:
	global_load_dword v2, v0, s[4:5] sc1
	s_waitcnt vmcnt(0)
	v_readfirstlane_b32 s9, v2
	s_nop 3
	s_cmp_ge_u32 s9, 1
	s_cbranch_scc1 .Lgb1_done
	s_sleep 1
	s_branch .Lgb1_loop

; #define SEAM(k) do { if (IN(k) && IN((k) + 1)) grid.sync(); } while (0)
; __global__ void __launch_bounds__(512, 2) mega(Args args) {
;     ...
;     SEAM(2);
.LBB0_303:
	v_readlane_b32 s0, v252, 22
	v_readlane_b32 s3, v252, 25
	v_readlane_b32 s1, v252, 23
	s_cmp_gt_i32 s3, 3
	v_readlane_b32 s2, v252, 24
	s_cselect_b64 s[0:1], -1, 0
	s_and_b64 s[2:3], s[8:9], s[0:1]
	s_andn2_b64 vcc, exec, s[2:3]
	s_cbranch_vccnz .LBB0_315
	s_waitcnt vmcnt(0)
	v_or_b32_e32 v0, v213, v177
	s_movk_i32 s2, 0x3ff
	v_and_or_b32 v0, v0, s2, v176
	v_cmp_eq_u32_e32 vcc, 0, v0
	s_barrier
	s_and_saveexec_b64 s[2:3], vcc
	s_cbranch_execz .LBB0_314
	buffer_wbl2 sc1
	s_waitcnt vmcnt(0)
	v_readlane_b32 s4, v252, 22
	v_readlane_b32 s5, v252, 23
	s_and_b32 s6, s95, 7
	s_lshl_b32 s7, s6, 8
	s_add_i32 s7, s7, 0x80
	v_mov_b32_e32 v0, s7
	v_mov_b32_e32 v1, 1
	s_nop 3
	global_atomic_add v2, v0, v1, s[4:5] sc0
	s_sub_i32 s8, s76, s6
	s_add_i32 s8, s8, 7
	s_lshr_b32 s8, s8, 3
	s_mul_i32 s8, s8, 2
	s_waitcnt vmcnt(0)
	v_readfirstlane_b32 s9, v2
	s_nop 3
	s_add_i32 s9, s9, 1
	s_cmp_lg_u32 s9, s8
	s_cbranch_scc1 .Lgb2_poll
	v_mov_b32_e32 v0, 0x880
	global_atomic_add v2, v0, v1, s[4:5] sc0
	s_waitcnt vmcnt(0)
	v_readfirstlane_b32 s9, v2
	s_nop 3
	s_add_i32 s9, s9, 1
	s_cmp_lg_u32 s9, 16
	s_cbranch_scc1 .Lgb2_poll
	v_mov_b32_e32 v0, 0x980
	s_nop 0
	global_atomic_add v0, v1, s[4:5]

; #define SEAM(k) do { if (IN(k) && IN((k) + 1)) grid.sync(); } while (0)
; __global__ void __launch_bounds__(512, 2) mega(Args args) {
;     ...
;     SEAM(2);
.Lgb2_loop:
	global_load_dword v2, v0, s[4:5] sc1
	s_waitcnt vmcnt(0)
	v_readfirstlane_b32 s9, v2
	s_nop 3
	s_cmp_ge_u32 s9, 2
	s_cbranch_scc1 .Lgb2_done
	s_sleep 1
	s_branch .Lgb2_loop

; #define SEAM(k) do { if (IN(k) && IN((k) + 1)) grid.sync(); } while (0)
; __global__ void __launch_bounds__(512, 2) mega(Args args) {
;     ...
;     SEAM(3);
.LBB0_479:
	s_cmp_gt_i32 s71, 4
	s_cselect_b64 s[0:1], -1, 0
	s_and_b64 s[2:3], s[4:5], s[0:1]
	s_andn2_b64 vcc, exec, s[2:3]
	s_cbranch_vccnz .LBB0_491
	s_waitcnt vmcnt(0)
	v_or_b32_e32 v0, v213, v177
	s_movk_i32 s2, 0x3ff
	v_and_or_b32 v0, v0, s2, v176
	v_cmp_eq_u32_e32 vcc, 0, v0
	s_barrier
	s_and_saveexec_b64 s[2:3], vcc
	s_cbranch_execz .LBB0_490
	buffer_wbl2 sc1
	s_waitcnt vmcnt(0)
	v_readlane_b32 s4, v252, 22
	v_readlane_b32 s5, v252, 23
	s_and_b32 s6, s95, 7
	s_lshl_b32 s7, s6, 8
	s_add_i32 s7, s7, 0x80
	v_mov_b32_e32 v0, s7
	v_mov_b32_e32 v1, 1
	s_nop 3
	global_atomic_add v2, v0, v1, s[4:5] sc0
	s_sub_i32 s8, s76, s6
	s_add_i32 s8, s8, 7
	s_lshr_b32 s8, s8, 3
	s_mul_i32 s8, s8, 3
	s_waitcnt vmcnt(0)
	v_readfirstlane_b32 s9, v2
	s_nop 3
	s_add_i32 s9, s9, 1
	s_cmp_lg_u32 s9, s8
	s_cbranch_scc1 .Lgb3_poll
	v_mov_b32_e32 v0, 0x880
	global_atomic_add v2, v0, v1, s[4:5] sc0
	s_waitcnt vmcnt(0)
	v_readfirstlane_b32 s9, v2
	s_nop 3
	s_add_i32 s9, s9, 1
	s_cmp_lg_u32 s9, 24
	s_cbranch_scc1 .Lgb3_poll
	v_mov_b32_e32 v0, 0x980
	s_nop 0
	global_atomic_add v0, v1, s[4:5]

; #define SEAM(k) do { if (IN(k) && IN((k) + 1)) grid.sync(); } while (0)
; __global__ void __launch_bounds__(512, 2) mega(Args args) {
;     ...
;     SEAM(3);
.Lgb3_loop:
	global_load_dword v2, v0, s[4:5] sc1
	s_waitcnt vmcnt(0)
	v_readfirstlane_b32 s9, v2
	s_nop 3
	s_cmp_ge_u32 s9, 3
	s_cbranch_scc1 .Lgb3_done
	s_sleep 1
	s_branch .Lgb3_loop

; #define SEAM(k) do { if (IN(k) && IN((k) + 1)) grid.sync(); } while (0)
; __global__ void __launch_bounds__(512, 2) mega(Args args) {
;     ...
;     SEAM(4);
.LBB0_508:
	s_cmp_gt_i32 s71, 5
	s_cselect_b64 s[0:1], -1, 0
	s_and_b64 s[2:3], s[30:31], s[0:1]
	s_andn2_b64 vcc, exec, s[2:3]
	s_cbranch_vccnz .LBB0_520
	s_waitcnt vmcnt(0)
	v_or_b32_e32 v0, v213, v177
	s_movk_i32 s2, 0x3ff
	v_and_or_b32 v0, v0, s2, v176
	v_cmp_eq_u32_e32 vcc, 0, v0
	s_barrier
	s_and_saveexec_b64 s[2:3], vcc
	s_cbranch_execz .LBB0_519
	buffer_wbl2 sc1
	s_waitcnt vmcnt(0)
	v_readlane_b32 s4, v252, 22
	v_readlane_b32 s5, v252, 23
	s_and_b32 s6, s95, 7
	s_lshl_b32 s7, s6, 8
	s_add_i32 s7, s7, 0x80
	v_mov_b32_e32 v0, s7
	v_mov_b32_e32 v1, 1
	s_nop 3
	global_atomic_add v2, v0, v1, s[4:5] sc0
	s_sub_i32 s8, s76, s6
	s_add_i32 s8, s8, 7
	s_lshr_b32 s8, s8, 3
	s_mul_i32 s8, s8, 4
	s_waitcnt vmcnt(0)
	v_readfirstlane_b32 s9, v2
	s_nop 3
	s_add_i32 s9, s9, 1
	s_cmp_lg_u32 s9, s8
	s_cbranch_scc1 .Lgb4_poll
	v_mov_b32_e32 v0, 0x880
	global_atomic_add v2, v0, v1, s[4:5] sc0
	s_waitcnt vmcnt(0)
	v_readfirstlane_b32 s9, v2
	s_nop 3
	s_add_i32 s9, s9, 1
	s_cmp_lg_u32 s9, 32
	s_cbranch_scc1 .Lgb4_poll
	v_mov_b32_e32 v0, 0x980
	s_nop 0
	global_atomic_add v0, v1, s[4:5]

; #define SEAM(k) do { if (IN(k) && IN((k) + 1)) grid.sync(); } while (0)
; __global__ void __launch_bounds__(512, 2) mega(Args args) {
;     ...
;     SEAM(4);
.Lgb4_loop:
	global_load_dword v2, v0, s[4:5] sc1
	s_waitcnt vmcnt(0)
	v_readfirstlane_b32 s9, v2
	s_nop 3
	s_cmp_ge_u32 s9, 4
	s_cbranch_scc1 .Lgb4_done
	s_sleep 1
	s_branch .Lgb4_loop

; #define SEAM(k) do { if (IN(k) && IN((k) + 1)) grid.sync(); } while (0)
; __global__ void __launch_bounds__(512, 2) mega(Args args) {
;     ...
;     SEAM(5);
.LBB0_560:
	s_cmp_gt_i32 s71, 6
	s_cselect_b64 s[0:1], -1, 0
	s_and_b64 s[2:3], s[2:3], s[0:1]
	s_andn2_b64 vcc, exec, s[2:3]
	s_cbranch_vccnz .LBB0_572
	s_waitcnt vmcnt(0)
	v_or_b32_e32 v0, v213, v177
	s_movk_i32 s2, 0x3ff
	v_and_or_b32 v0, v0, s2, v176
	v_cmp_eq_u32_e32 vcc, 0, v0
	s_barrier
	s_and_saveexec_b64 s[2:3], vcc
	s_cbranch_execz .LBB0_571
	buffer_wbl2 sc1
	s_waitcnt vmcnt(0)
	v_readlane_b32 s4, v252, 22
	v_readlane_b32 s5, v252, 23
	s_and_b32 s6, s95, 7
	s_lshl_b32 s7, s6, 8
	s_add_i32 s7, s7, 0x80
	v_mov_b32_e32 v0, s7
	v_mov_b32_e32 v1, 1
	s_nop 3
	global_atomic_add v2, v0, v1, s[4:5] sc0
	s_sub_i32 s8, s76, s6
	s_add_i32 s8, s8, 7
	s_lshr_b32 s8, s8, 3
	s_mul_i32 s8, s8, 5
	s_waitcnt vmcnt(0)
	v_readfirstlane_b32 s9, v2
	s_nop 3
	s_add_i32 s9, s9, 1
	s_cmp_lg_u32 s9, s8
	s_cbranch_scc1 .Lgb5_poll
	v_mov_b32_e32 v0, 0x880
	global_atomic_add v2, v0, v1, s[4:5] sc0
	s_waitcnt vmcnt(0)
	v_readfirstlane_b32 s9, v2
	s_nop 3
	s_add_i32 s9, s9, 1
	s_cmp_lg_u32 s9, 40
	s_cbranch_scc1 .Lgb5_poll
	v_mov_b32_e32 v0, 0x980
	s_nop 0
	global_atomic_add v0, v1, s[4:5]

; #define SEAM(k) do { if (IN(k) && IN((k) + 1)) grid.sync(); } while (0)
; __global__ void __launch_bounds__(512, 2) mega(Args args) {
;     ...
;     SEAM(5);
.Lgb5_loop:
	global_load_dword v2, v0, s[4:5] sc1
	s_waitcnt vmcnt(0)
	v_readfirstlane_b32 s9, v2
	s_nop 3
	s_cmp_ge_u32 s9, 5
	s_cbranch_scc1 .Lgb5_done
	s_sleep 1
	s_branch .Lgb5_loop

; #define SEAM(k) do { if (IN(k) && IN((k) + 1)) grid.sync(); } while (0)
; __global__ void __launch_bounds__(512, 2) mega(Args args) {
;     ...
;     SEAM(6);
.LBB0_607:
	s_cmp_gt_i32 s71, 7
	s_cselect_b64 s[0:1], -1, 0
	s_and_b64 s[2:3], s[4:5], s[0:1]
	s_andn2_b64 vcc, exec, s[2:3]
	s_cbranch_vccnz .LBB0_619
	s_waitcnt vmcnt(0)
	v_or_b32_e32 v0, v213, v177
	s_movk_i32 s2, 0x3ff
	v_and_or_b32 v0, v0, s2, v176
	v_cmp_eq_u32_e32 vcc, 0, v0
	s_waitcnt lgkmcnt(0)
	s_barrier
	s_and_saveexec_b64 s[2:3], vcc
	s_cbranch_execz .LBB0_618
	buffer_wbl2 sc1
	s_waitcnt vmcnt(0)
	v_readlane_b32 s4, v252, 22
	v_readlane_b32 s5, v252, 23
	s_and_b32 s6, s95, 7
	s_lshl_b32 s7, s6, 8
	s_add_i32 s7, s7, 0x80
	v_mov_b32_e32 v0, s7
	v_mov_b32_e32 v1, 1
	s_nop 3
	global_atomic_add v2, v0, v1, s[4:5] sc0
	s_sub_i32 s8, s76, s6
	s_add_i32 s8, s8, 7
	s_lshr_b32 s8, s8, 3
	s_mul_i32 s8, s8, 6
	s_waitcnt vmcnt(0)
	v_readfirstlane_b32 s9, v2
	s_nop 3
	s_add_i32 s9, s9, 1
	s_cmp_lg_u32 s9, s8
	s_cbranch_scc1 .Lgb6_poll
	v_mov_b32_e32 v0, 0x880
	global_atomic_add v2, v0, v1, s[4:5] sc0
	s_waitcnt vmcnt(0)
	v_readfirstlane_b32 s9, v2
	s_nop 3
	s_add_i32 s9, s9, 1
	s_cmp_lg_u32 s9, 48
	s_cbranch_scc1 .Lgb6_poll
	v_mov_b32_e32 v0, 0x980
	s_nop 0
	global_atomic_add v0, v1, s[4:5]

; #define SEAM(k) do { if (IN(k) && IN((k) + 1)) grid.sync(); } while (0)
; __global__ void __launch_bounds__(512, 2) mega(Args args) {
;     ...
;     SEAM(6);
.Lgb6_loop:
	global_load_dword v2, v0, s[4:5] sc1
	s_waitcnt vmcnt(0)
	v_readfirstlane_b32 s9, v2
	s_nop 3
	s_cmp_ge_u32 s9, 6
	s_cbranch_scc1 .Lgb6_done
	s_sleep 1
	s_branch .Lgb6_loop

; #define SEAM(k) do { if (IN(k) && IN((k) + 1)) grid.sync(); } while (0)
; __global__ void __launch_bounds__(512, 2) mega(Args args) {
;     ...
;     SEAM(7);
.LBB0_693:
	s_cmp_gt_i32 s71, 8
	s_cselect_b64 s[0:1], -1, 0
	s_and_b64 s[2:3], s[10:11], s[0:1]
	s_andn2_b64 vcc, exec, s[2:3]
	s_cbranch_vccnz .LBB0_705
	s_waitcnt vmcnt(0)
	v_or_b32_e32 v0, v213, v177
	s_movk_i32 s2, 0x3ff
	v_and_or_b32 v0, v0, s2, v176
	v_cmp_eq_u32_e32 vcc, 0, v0
	s_waitcnt lgkmcnt(0)
	s_barrier
	s_and_saveexec_b64 s[2:3], vcc
	s_cbranch_execz .LBB0_704
	buffer_wbl2 sc1
	s_waitcnt vmcnt(0)
	v_readlane_b32 s4, v252, 22
	v_readlane_b32 s5, v252, 23
	s_and_b32 s6, s95, 7
	s_lshl_b32 s7, s6, 8
	s_add_i32 s7, s7, 0x80
	v_mov_b32_e32 v0, s7
	v_mov_b32_e32 v1, 1
	s_nop 3
	global_atomic_add v2, v0, v1, s[4:5] sc0
	s_sub_i32 s8, s76, s6
	s_add_i32 s8, s8, 7
	s_lshr_b32 s8, s8, 3
	s_mul_i32 s8, s8, 7
	s_waitcnt vmcnt(0)
	v_readfirstlane_b32 s9, v2
	s_nop 3
	s_add_i32 s9, s9, 1
	s_cmp_lg_u32 s9, s8
	s_cbranch_scc1 .Lgb7_poll
	v_mov_b32_e32 v0, 0x880
	global_atomic_add v2, v0, v1, s[4:5] sc0
	s_waitcnt vmcnt(0)
	v_readfirstlane_b32 s9, v2
	s_nop 3
	s_add_i32 s9, s9, 1
	s_cmp_lg_u32 s9, 56
	s_cbranch_scc1 .Lgb7_poll
	v_mov_b32_e32 v0, 0x980
	s_nop 0
	global_atomic_add v0, v1, s[4:5]

; #define SEAM(k) do { if (IN(k) && IN((k) + 1)) grid.sync(); } while (0)
; __global__ void __launch_bounds__(512, 2) mega(Args args) {
;     ...
;     SEAM(7);
.Lgb7_loop:
	global_load_dword v2, v0, s[4:5] sc1
	s_waitcnt vmcnt(0)
	v_readfirstlane_b32 s9, v2
	s_nop 3
	s_cmp_ge_u32 s9, 7
	s_cbranch_scc1 .Lgb7_done
	s_sleep 1
	s_branch .Lgb7_loop
